# v36 + nt on the f32 MLA cache loads of the sample attention units
# speedup vs baseline: 1.0058x; 1.0058x over previous
.LBB0_1017:
	s_and_b64 vcc, exec, s[8:9]
	s_cbranch_vccz .LBB0_862
	s_lshl_b32 s4, s33, 3
	s_ashr_i32 s14, s33, 1
	v_and_or_b32 v203, s4, 8, v199
	v_lshl_or_b32 v194, s14, 4, v200
	v_mov_b64_e32 v[0:1], s[56:57]
	v_mul_u32_u24_e32 v2, 0x120, v203
	v_mov_b32_e32 v22, v210
	v_mad_i64_i32 v[0:1], s[4:5], v194, s87, v[0:1]
	v_lshlrev_b32_e32 v192, 1, v2
	v_lshl_add_u64 v[0:1], v[0:1], 0, v[192:193]
	v_bfe_u32 v23, v22, 5, 1
	v_lshlrev_b32_e32 v16, 4, v23
	v_mov_b32_e32 v17, v193
	v_lshl_add_u64 v[0:1], v[0:1], 0, v[16:17]
	global_load_dwordx4 v[80:83], v[0:1], off
	global_load_dwordx4 v[84:87], v[0:1], off offset:32
	global_load_dwordx4 v[88:91], v[0:1], off offset:64
	global_load_dwordx4 v[92:95], v[0:1], off offset:96
	global_load_dwordx4 v[96:99], v[0:1], off offset:128
	global_load_dwordx4 v[100:103], v[0:1], off offset:160
	global_load_dwordx4 v[104:107], v[0:1], off offset:192
	global_load_dwordx4 v[108:111], v[0:1], off offset:224
	global_load_dwordx4 v[112:115], v[0:1], off offset:256
	global_load_dwordx4 v[116:119], v[0:1], off offset:288
	global_load_dwordx4 v[120:123], v[0:1], off offset:320
	global_load_dwordx4 v[124:127], v[0:1], off offset:352
	global_load_dwordx4 v[128:131], v[0:1], off offset:384
	global_load_dwordx4 v[132:135], v[0:1], off offset:416
	global_load_dwordx4 v[136:139], v[0:1], off offset:448
	global_load_dwordx4 v[140:143], v[0:1], off offset:480
	global_load_dwordx4 v[144:147], v[0:1], off offset:512
	global_load_dwordx4 v[148:151], v[0:1], off offset:544
	s_ashr_i32 s15, s14, 31
	s_lshl_b64 s[4:5], s[14:15], 22
	s_add_u32 s18, s20, s4
	s_addc_u32 s19, s21, s5
	s_lshl_b64 s[4:5], s[14:15], 19
	s_add_u32 s12, s22, s4
	s_addc_u32 s13, s23, s5
	s_lshl_b64 s[4:5], s[14:15], 14
	s_add_u32 s33, s72, s4
	v_ashrrev_i32_e32 v204, 5, v22
	v_add_u32_e32 v8, 0x200, v22
	s_addc_u32 s46, s73, s5
	v_min_i32_e32 v0, 0x100f, v204
	v_ashrrev_i32_e32 v205, 5, v8
	v_add_u32_e32 v2, 0xfffff000, v0
	v_ashrrev_i32_e32 v1, 31, v0
	v_cmp_gt_i32_e32 vcc, s88, v204
	v_mov_b32_e32 v10, s46
	v_mov_b32_e32 v11, s19
	v_mov_b32_e32 v12, s33
	v_mov_b32_e32 v13, s18
	v_min_i32_e32 v8, 0x100f, v205
	v_cndmask_b32_e32 v1, 0, v1, vcc
	v_cndmask_b32_e32 v0, v2, v0, vcc
	v_cndmask_b32_e32 v3, v10, v11, vcc
	v_cndmask_b32_e32 v2, v12, v13, vcc
	v_ashrrev_i32_e32 v9, 31, v8
	v_add_u32_e32 v14, 0xfffff000, v8
	v_cmp_gt_i32_e32 vcc, s88, v205
	v_lshlrev_b32_e32 v19, 3, v22
	v_and_b32_e32 v4, 0xf8, v19
	v_cndmask_b32_e32 v9, 0, v9, vcc
	v_cndmask_b32_e32 v8, v14, v8, vcc
	v_lshlrev_b64 v[0:1], 10, v[0:1]
	v_cndmask_b32_e32 v11, v10, v11, vcc
	v_cndmask_b32_e32 v10, v12, v13, vcc
	v_lshlrev_b64 v[8:9], 10, v[8:9]
	v_lshl_add_u64 v[0:1], v[2:3], 0, v[0:1]
	v_lshlrev_b32_e32 v192, 2, v4
	v_lshl_add_u64 v[8:9], v[10:11], 0, v[8:9]
	v_lshl_add_u64 v[4:5], v[0:1], 0, v[192:193]
	v_lshl_add_u64 v[12:13], v[8:9], 0, v[192:193]
	global_load_dwordx4 v[0:3], v[4:5], off offset:16 nt
	s_nop 0
	global_load_dwordx4 v[4:7], v[4:5], off nt
	s_nop 0
	global_load_dwordx4 v[8:11], v[12:13], off offset:16 nt
	s_nop 0
	global_load_dwordx4 v[12:15], v[12:13], off nt
	v_lshlrev_b32_e32 v17, 2, v22
	v_and_b32_e32 v196, 28, v17
	v_cmp_lt_i32_e64 s[10:11], s81, v22
	v_cmp_gt_i32_e64 s[8:9], s82, v22
	v_ashrrev_i32_e32 v18, 3, v22
	v_lshlrev_b32_e32 v20, 2, v196
	s_and_saveexec_b64 s[16:17], s[8:9]
	s_cbranch_execz .LBB0_1020
	v_ashrrev_i32_e32 v24, 3, v22
	v_ashrrev_i32_e32 v25, 31, v24
	v_lshlrev_b64 v[24:25], 7, v[24:25]
	v_lshl_add_u64 v[24:25], s[12:13], 0, v[24:25]
	v_mov_b32_e32 v21, v193
	v_lshl_add_u64 v[24:25], v[24:25], 0, v[20:21]
	global_load_dwordx4 v[152:155], v[24:25], off nt
.LBB0_1020:
	s_or_b64 exec, exec, s[16:17]
	v_min_i32_e32 v21, 0xfef, v204
	v_add_u32_e32 v24, 0xfffff020, v21
	v_add_u32_e32 v21, 32, v21
	v_ashrrev_i32_e32 v25, 31, v21
	v_cmp_gt_i32_e32 vcc, s89, v204
	v_mov_b32_e32 v28, s19
	v_mov_b32_e32 v29, s33
	v_cndmask_b32_e32 v25, 0, v25, vcc
	v_cndmask_b32_e32 v24, v24, v21, vcc
	v_mov_b32_e32 v21, s46
	v_mov_b32_e32 v30, s18
	v_cndmask_b32_e32 v27, v21, v28, vcc
	v_cndmask_b32_e32 v26, v29, v30, vcc
	v_lshlrev_b64 v[24:25], 10, v[24:25]
	v_lshl_add_u64 v[24:25], v[26:27], 0, v[24:25]
	v_lshl_add_u64 v[24:25], v[24:25], 0, v[192:193]
	global_load_dwordx4 v[156:159], v[24:25], off offset:16 nt
	global_load_dwordx4 v[160:163], v[24:25], off nt
	v_min_i32_e32 v24, 0xfef, v205
	v_add_u32_e32 v26, 32, v24
	v_ashrrev_i32_e32 v25, 31, v26
	v_add_u32_e32 v24, 0xfffff020, v24
	v_cmp_gt_i32_e32 vcc, s89, v205
	s_nop 1
	v_cndmask_b32_e32 v25, 0, v25, vcc
	v_cndmask_b32_e32 v24, v24, v26, vcc
	v_cndmask_b32_e32 v27, v21, v28, vcc
	v_cndmask_b32_e32 v26, v29, v30, vcc
	v_lshlrev_b64 v[24:25], 10, v[24:25]
	v_lshl_add_u64 v[24:25], v[26:27], 0, v[24:25]
	v_lshl_add_u64 v[24:25], v[24:25], 0, v[192:193]
	global_load_dwordx4 v[168:171], v[24:25], off offset:16 nt
	global_load_dwordx4 v[172:175], v[24:25], off nt
	s_and_saveexec_b64 s[16:17], s[8:9]
	s_cbranch_execz .LBB0_1022
	v_ashrrev_i32_e32 v24, 3, v22
	v_ashrrev_i32_e32 v25, 31, v24
	v_lshlrev_b64 v[24:25], 7, v[24:25]
	v_lshl_add_u64 v[24:25], s[12:13], 0, v[24:25]
	v_mov_b32_e32 v21, v193
	v_lshl_add_u64 v[24:25], v[24:25], 0, v[20:21]
	v_add_co_u32_e32 v24, vcc, 0x1000, v24
	s_nop 1
	v_addc_co_u32_e32 v25, vcc, 0, v25, vcc
	global_load_dwordx4 v[164:167], v[24:25], off nt

.LBB0_1024:
	s_or_b64 exec, exec, s[16:17]
	v_min_i32_e32 v0, 0xfcf, v204
	v_add_u32_e32 v2, 0xfffff040, v0
	v_add_u32_e32 v0, 64, v0
	v_ashrrev_i32_e32 v1, 31, v0
	v_cmp_gt_i32_e32 vcc, s91, v204
	v_mov_b32_e32 v4, s46
	v_mov_b32_e32 v5, s19
	v_cndmask_b32_e32 v1, 0, v1, vcc
	v_cndmask_b32_e32 v0, v2, v0, vcc
	v_mov_b32_e32 v6, s33
	v_mov_b32_e32 v7, s18
	v_cndmask_b32_e32 v3, v4, v5, vcc
	v_cndmask_b32_e32 v2, v6, v7, vcc
	v_lshlrev_b64 v[0:1], 10, v[0:1]
	v_lshl_add_u64 v[0:1], v[2:3], 0, v[0:1]
	v_lshl_add_u64 v[0:1], v[0:1], 0, v[192:193]
	global_load_dwordx4 v[176:179], v[0:1], off offset:16 nt
	global_load_dwordx4 v[180:183], v[0:1], off nt
	v_min_i32_e32 v0, 0xfcf, v205
	v_add_u32_e32 v2, 64, v0
	v_ashrrev_i32_e32 v1, 31, v2
	v_add_u32_e32 v0, 0xfffff040, v0
	v_cmp_gt_i32_e32 vcc, s91, v205
	s_nop 1
	v_cndmask_b32_e32 v1, 0, v1, vcc
	v_cndmask_b32_e32 v0, v0, v2, vcc
	v_cndmask_b32_e32 v3, v4, v5, vcc
	v_cndmask_b32_e32 v2, v6, v7, vcc
	v_lshlrev_b64 v[0:1], 10, v[0:1]
	v_lshl_add_u64 v[0:1], v[2:3], 0, v[0:1]
	v_lshl_add_u64 v[0:1], v[0:1], 0, v[192:193]
	global_load_dwordx4 v[184:187], v[0:1], off offset:16 nt
	global_load_dwordx4 v[188:191], v[0:1], off nt
	s_and_saveexec_b64 s[4:5], s[10:11]
	s_xor_b64 s[10:11], exec, s[4:5]
	v_mov_b32_e32 v197, v193
	s_andn2_saveexec_b64 s[10:11], s[10:11]
	s_cbranch_execz .LBB0_1028
	v_ashrrev_i32_e32 v19, 31, v18
	v_lshlrev_b64 v[0:1], 7, v[18:19]
	v_lshl_add_u64 v[0:1], s[12:13], 0, v[0:1]
	v_mov_b32_e32 v21, v193
	v_lshl_add_u64 v[0:1], v[0:1], 0, v[20:21]
	v_add_co_u32_e32 v0, vcc, 0x2000, v0
	v_mov_b32_e32 v197, v193
	s_nop 0
	v_addc_co_u32_e32 v1, vcc, 0, v1, vcc
	global_load_dwordx4 v[152:155], v[0:1], off nt
	v_mov_b32_e32 v209, v18

.LBB0_1035:
	s_cmpk_gt_u32 s50, 0x7d
	s_cbranch_scc1 .LBB0_1039
	s_waitcnt vmcnt(3)
	v_add_u32_e32 v156, s47, v204
	v_add_u32_e32 v156, 0x60, v156
	s_waitcnt vmcnt(1)
	v_add_u32_e32 v168, s47, v205
	v_min_i32_e32 v158, 0x100f, v156
	v_add_u32_e32 v168, 0x60, v168
	v_add_u32_e32 v159, 0xfffff000, v158
	v_ashrrev_i32_e32 v157, 31, v158
	v_cmp_gt_i32_e32 vcc, s88, v156
	v_mov_b32_e32 v170, s46
	v_mov_b32_e32 v171, s19
	s_waitcnt vmcnt(0)
	v_mov_b32_e32 v172, s33
	v_mov_b32_e32 v173, s18
	v_min_i32_e32 v174, 0x100f, v168
	v_cndmask_b32_e32 v157, 0, v157, vcc
	v_cndmask_b32_e32 v156, v159, v158, vcc
	v_cndmask_b32_e32 v159, v170, v171, vcc
	v_cndmask_b32_e32 v158, v172, v173, vcc
	v_ashrrev_i32_e32 v169, 31, v174
	v_add_u32_e32 v175, 0xfffff000, v174
	v_cmp_gt_i32_e32 vcc, s88, v168
	v_lshlrev_b64 v[156:157], 10, v[156:157]
	v_lshl_add_u64 v[156:157], v[158:159], 0, v[156:157]
	v_cndmask_b32_e32 v169, 0, v169, vcc
	v_cndmask_b32_e32 v168, v175, v174, vcc
	v_cndmask_b32_e32 v171, v170, v171, vcc
	v_cndmask_b32_e32 v170, v172, v173, vcc
	v_lshlrev_b64 v[168:169], 10, v[168:169]
	v_lshl_add_u64 v[168:169], v[170:171], 0, v[168:169]
	v_lshl_add_u64 v[160:161], v[156:157], 0, v[192:193]
	v_lshl_add_u64 v[172:173], v[168:169], 0, v[192:193]
	global_load_dwordx4 v[156:159], v[160:161], off offset:16 nt
	s_nop 0
	global_load_dwordx4 v[160:163], v[160:161], off nt
	s_nop 0
	global_load_dwordx4 v[168:171], v[172:173], off offset:16 nt
	s_nop 0
	global_load_dwordx4 v[172:175], v[172:173], off nt
	s_and_saveexec_b64 s[14:15], s[8:9]
	s_cbranch_execz .LBB0_1038
	v_add_u32_e32 v164, s47, v209
	v_add_u32_e32 v164, 0x60, v164
	v_min_i32_e32 v166, 0x100f, v164
	v_add_u32_e32 v167, 0xfffff000, v166
	v_cmp_gt_i32_e32 vcc, s88, v164
	v_ashrrev_i32_e32 v165, 31, v166
	v_mov_b32_e32 v218, s12
	v_cndmask_b32_e32 v164, v167, v166, vcc
	v_mov_b32_e32 v166, s17
	v_mov_b32_e32 v167, s13
	v_cndmask_b32_e32 v165, 0, v165, vcc
	v_cndmask_b32_e32 v167, v166, v167, vcc
	v_mov_b32_e32 v166, s16
	v_cndmask_b32_e32 v166, v166, v218, vcc
	v_lshlrev_b64 v[164:165], 7, v[164:165]
	v_lshl_add_u64 v[164:165], v[166:167], 0, v[164:165]
	v_lshl_add_u64 v[164:165], v[196:197], 2, v[164:165]
	global_load_dwordx4 v[164:167], v[164:165], off nt

.LBB0_1042:
	v_sub_f32_e32 v64, v64, v217
	v_sub_f32_e32 v65, v65, v217
	v_sub_f32_e32 v66, v66, v217
	v_sub_f32_e32 v67, v67, v217
	v_sub_f32_e32 v68, v68, v217
	v_sub_f32_e32 v69, v69, v217
	v_sub_f32_e32 v70, v70, v217
	v_sub_f32_e32 v71, v71, v217
	v_exp_f32_e32 v64, v64
	v_exp_f32_e32 v65, v65
	v_exp_f32_e32 v66, v66
	v_exp_f32_e32 v67, v67
	v_exp_f32_e32 v68, v68
	v_exp_f32_e32 v69, v69
	v_exp_f32_e32 v70, v70
	v_exp_f32_e32 v71, v71
	ds_read_b64_tr_b16 v[226:227], v216 offset:18944
	ds_read_b64_tr_b16 v[228:229], v216 offset:23680
	ds_read_b64_tr_b16 v[230:231], v216 offset:28416
	ds_read_b64_tr_b16 v[232:233], v216 offset:33152
	ds_read_b64_tr_b16 v[234:235], v216 offset:19008
	ds_read_b64_tr_b16 v[238:239], v216 offset:19072
	ds_read_b64_tr_b16 v[242:243], v216 offset:19136
	ds_read_b64_tr_b16 v[236:237], v216 offset:23744
	ds_read_b64_tr_b16 v[240:241], v216 offset:23808
	ds_read_b64_tr_b16 v[244:245], v216 offset:23872
	v_cvt_pk_bf16_f32 v218, v64, v65
	v_cvt_pk_bf16_f32 v219, v66, v67
	v_cvt_pk_bf16_f32 v220, v68, v69
	v_cvt_pk_bf16_f32 v221, v70, v71
	v_sub_f32_e32 v72, v72, v217
	v_sub_f32_e32 v73, v73, v217
	s_waitcnt lgkmcnt(8)
	v_mfma_f32_32x32x16_bf16 v[48:63], v[226:229], v[218:221], v[48:63]
	v_sub_f32_e32 v74, v74, v217
	v_sub_f32_e32 v75, v75, v217
	v_sub_f32_e32 v76, v76, v217
	v_sub_f32_e32 v77, v77, v217
	v_sub_f32_e32 v78, v78, v217
	v_sub_f32_e32 v79, v79, v217
	v_exp_f32_e32 v72, v72
	s_waitcnt lgkmcnt(2)
	v_mfma_f32_32x32x16_bf16 v[32:47], v[234:237], v[218:221], v[32:47]
	v_exp_f32_e32 v73, v73
	v_exp_f32_e32 v74, v74
	v_exp_f32_e32 v75, v75
	v_exp_f32_e32 v76, v76
	v_exp_f32_e32 v77, v77
	v_exp_f32_e32 v78, v78
	v_exp_f32_e32 v79, v79
	s_waitcnt lgkmcnt(1)
	v_mfma_f32_32x32x16_bf16 v[16:31], v[238:241], v[218:221], v[16:31]
	ds_read_b64_tr_b16 v[226:227], v216 offset:28480
	ds_read_b64_tr_b16 v[246:247], v216 offset:28544
	ds_read_b64_tr_b16 v[250:251], v216 offset:28608
	ds_read_b64_tr_b16 v[228:229], v216 offset:33216
	ds_read_b64_tr_b16 v[248:249], v216 offset:33280
	ds_read_b64_tr_b16 v[252:253], v216 offset:33344
	v_cvt_pk_bf16_f32 v222, v72, v73
	v_cvt_pk_bf16_f32 v223, v74, v75
	v_cvt_pk_bf16_f32 v224, v76, v77
	v_cvt_pk_bf16_f32 v225, v78, v79
	s_waitcnt lgkmcnt(6)
	v_mfma_f32_32x32x16_bf16 v[0:15], v[242:245], v[218:221], v[0:15]
	s_waitcnt vmcnt(2)
	v_cvt_pk_bf16_f32 v218, v180, v181
	v_cvt_pk_bf16_f32 v219, v182, v183
	v_cvt_pk_bf16_f32 v220, v176, v177
	v_cvt_pk_bf16_f32 v221, v178, v179
	ds_write_b128 v206, v[218:221]
	s_waitcnt vmcnt(0)
	v_cvt_pk_bf16_f32 v218, v188, v189
	v_cvt_pk_bf16_f32 v219, v190, v191
	v_mfma_f32_32x32x16_bf16 v[48:63], v[230:233], v[222:225], v[48:63]
	v_cvt_pk_bf16_f32 v220, v184, v185
	v_cvt_pk_bf16_f32 v221, v186, v187
	ds_write_b128 v207, v[218:221]
	s_waitcnt lgkmcnt(4)
	v_mfma_f32_32x32x16_bf16 v[32:47], v[226:229], v[222:225], v[32:47]
	s_waitcnt lgkmcnt(3)
	v_mfma_f32_32x32x16_bf16 v[16:31], v[246:249], v[222:225], v[16:31]
	s_waitcnt lgkmcnt(2)
	v_mfma_f32_32x32x16_bf16 v[0:15], v[250:253], v[222:225], v[0:15]
	s_and_saveexec_b64 s[10:11], s[8:9]
	v_cvt_pk_bf16_f32 v218, v152, v153
	v_cvt_pk_bf16_f32 v219, v154, v155
	v_add_u32_e32 v220, v213, v208
	ds_write_b64 v220, v[218:219] offset:512
	s_or_b64 exec, exec, s[10:11]
	s_cmpk_gt_u32 s50, 0x7c
	s_cbranch_scc1 .LBB0_1048
	v_add_u32_e32 v176, s47, v204
	v_add_u32_e32 v176, 0x80, v176
	v_add_u32_e32 v184, s47, v205
	v_min_i32_e32 v178, 0x100f, v176
	v_add_u32_e32 v184, 0x80, v184
	v_add_u32_e32 v179, 0xfffff000, v178
	v_ashrrev_i32_e32 v177, 31, v178
	v_cmp_gt_i32_e32 vcc, s88, v176
	v_mov_b32_e32 v186, s46
	v_mov_b32_e32 v187, s19
	v_mov_b32_e32 v188, s33
	v_mov_b32_e32 v189, s18
	v_min_i32_e32 v190, 0x100f, v184
	v_cndmask_b32_e32 v177, 0, v177, vcc
	v_cndmask_b32_e32 v176, v179, v178, vcc
	v_cndmask_b32_e32 v179, v186, v187, vcc
	v_cndmask_b32_e32 v178, v188, v189, vcc
	v_ashrrev_i32_e32 v185, 31, v190
	v_add_u32_e32 v191, 0xfffff000, v190
	v_cmp_gt_i32_e32 vcc, s88, v184
	v_lshlrev_b64 v[176:177], 10, v[176:177]
	v_lshl_add_u64 v[176:177], v[178:179], 0, v[176:177]
	v_cndmask_b32_e32 v185, 0, v185, vcc
	v_cndmask_b32_e32 v184, v191, v190, vcc
	v_cndmask_b32_e32 v187, v186, v187, vcc
	v_cndmask_b32_e32 v186, v188, v189, vcc
	v_lshlrev_b64 v[184:185], 10, v[184:185]
	v_lshl_add_u64 v[184:185], v[186:187], 0, v[184:185]
	v_lshl_add_u64 v[180:181], v[176:177], 0, v[192:193]
	v_lshl_add_u64 v[188:189], v[184:185], 0, v[192:193]
	global_load_dwordx4 v[176:179], v[180:181], off offset:16 nt
	s_nop 0
	global_load_dwordx4 v[180:183], v[180:181], off nt
	s_nop 0
	global_load_dwordx4 v[184:187], v[188:189], off offset:16 nt
	s_nop 0
	global_load_dwordx4 v[188:191], v[188:189], off nt
	s_and_saveexec_b64 s[10:11], s[8:9]
	s_cbranch_execz .LBB0_1047
	v_add_u32_e32 v152, s47, v209
	v_add_u32_e32 v152, 0x80, v152
	v_min_i32_e32 v154, 0x100f, v152
	v_add_u32_e32 v155, 0xfffff000, v154
	v_cmp_gt_i32_e32 vcc, s88, v152
	v_ashrrev_i32_e32 v153, 31, v154
	v_mov_b32_e32 v218, s12
	v_cndmask_b32_e32 v152, v155, v154, vcc
	v_mov_b32_e32 v154, s17
	v_mov_b32_e32 v155, s13
	v_cndmask_b32_e32 v153, 0, v153, vcc
	v_cndmask_b32_e32 v155, v154, v155, vcc
	v_mov_b32_e32 v154, s16
	v_cndmask_b32_e32 v154, v154, v218, vcc
	v_lshlrev_b64 v[152:153], 7, v[152:153]
	v_lshl_add_u64 v[152:153], v[154:155], 0, v[152:153]
	v_lshl_add_u64 v[152:153], v[196:197], 2, v[152:153]
	global_load_dwordx4 v[152:155], v[152:153], off nt
